# early2+tail priority+faster wake, stacked with epilogue load hoists (P6,P13) and iteration-0 wait relaxation (P2,P13)
# baseline (speedup 1.0000x reference)
; #define PG8_STAGE(bufoff, gbase, voff) do { _Pragma("unroll") for (int _i = 0; _i < 2; ++_i) \
;         __builtin_amdgcn_global_load_lds((const unsigned*)((const char*)(gbase) + (voff)[_i]), (PG8_LAS unsigned*)(lds + (bufoff) + ldsw + _i * 8192), 16, 0, 0); } while (0)
; #define PG8_WAIT_V(n) asm volatile("s_waitcnt vmcnt(" #n ")" ::: "memory")
; #define PG8_BAR __builtin_amdgcn_s_barrier()
; template <class Epi, class Sched, bool ALIGN_EPI = false, bool SP2 = false>
; __device__ __forceinline__ void gemm_phase(PG8_LAS unsigned char* lds, const Gemm g, const Sched& S, const Epi& E) {
;     ...
;     if constexpr (SP2) {
;         PG8_STAGE(PG8_SB(0, 0), cB, voffB); PG8_STAGE(PG8_SB(0, 1), cB + hstep, voffB); PG8_STAGE(PG8_SA(0, 0), cA, voffA); PG8_STAGE(PG8_SA(0, 1), cA + hstep, voffA);
;         if (wr == 1) PG8_BAR;
;         PG8_WAIT_V(2); PG8_BAR;
;         PG8_STAGE(PG8_SB(1, 0), cB + kstep, voffB); PG8_STAGE(PG8_SA(1, 0), cA + kstep, voffA); PG8_STAGE(PG8_SB(1, 1), cB + hstep + kstep, voffB);
;         PG8_WAIT_V(6); PG8_BAR;
;     } else {
;         PG8_STAGE(PG8_SB(0, 0), cB, voffB); PG8_STAGE(PG8_SA(0, 0), cA, voffA); PG8_STAGE(PG8_SB(0, 1), cB + hstep, voffB); PG8_STAGE(PG8_SA(0, 1), cA + hstep, voffA);
;         if (wr == 1) PG8_BAR;
;         PG8_WAIT_V(4); PG8_BAR;
;         PG8_STAGE(PG8_SB(1, 0), cB + kstep, voffB); PG8_STAGE(PG8_SA(1, 0), cA + kstep, voffA); PG8_STAGE(PG8_SB(1, 1), cB + hstep + kstep, voffB);
;         PG8_WAIT_V(6); PG8_BAR;
;     }
.LBB0_1132:
	s_lshl_b32 s8, s8, 5
	s_and_b32 s14, s8, 0x60
	s_mov_b64 s[8:9], 0x80
	s_add_i32 m0, s41, 0x18000
	v_lshl_add_u64 v[6:7], v[6:7], 0, s[8:9]
	s_lshl_b32 s11, s1, 13
	s_lshl_b32 s15, s14, 7
	s_waitcnt vmcnt(2)
	s_barrier
	global_load_lds_dwordx4 v[6:7], off
	v_lshl_add_u64 v[4:5], v[4:5], 0, s[8:9]
	s_add_i32 m0, s41, 0x1a000
	s_add_i32 s52, s41, 0x8000
	s_add_i32 s53, s41, 0xa000
	global_load_lds_dwordx4 v[4:5], off
	v_lshl_add_u64 v[0:1], v[0:1], 0, s[8:9]
	s_mov_b32 m0, s52
	s_add_u32 s12, s44, 0x80080
	global_load_lds_dwordx4 v[0:1], off
	v_lshl_add_u64 v[0:1], v[2:3], 0, s[8:9]
	s_mov_b32 m0, s53
	s_addc_u32 s13, s45, 0
	global_load_lds_dwordx4 v[0:1], off
	s_add_i32 m0, s41, 0x1c000
	v_lshl_add_u64 v[0:1], s[12:13], 0, v[148:149]
	global_load_lds_dwordx4 v[0:1], off
	v_lshl_add_u64 v[0:1], s[12:13], 0, v[152:153]
	s_add_i32 m0, s41, 0x1e000
	v_lshlrev_b32_e32 v2, 2, v146
	global_load_lds_dwordx4 v[0:1], off
	v_and_b32_e32 v0, 15, v146
	v_lshlrev_b32_e32 v1, 1, v11
	v_lshl_or_b32 v168, s1, 6, v0
	v_lshl_or_b32 v0, v0, 6, v1
	v_and_b32_e32 v2, 32, v2
	s_sext_i32_i16 s59, s0
	v_bitop3_b32 v3, v0, s11, v2 bitop3:0xde
	v_lshlrev_b32_e32 v0, 6, v146
	s_movk_i32 s0, 0x3c0
	v_and_or_b32 v0, v0, s0, v1
	v_readlane_b32 s0, v252, 17
	v_bitop3_b32 v169, s15, v0, v2 bitop3:0xf6
	v_lshlrev_b32_e32 v0, 2, v11
	v_mov_b32_e32 v1, v149
	v_readlane_b32 s1, v252, 18
	s_waitcnt vmcnt(6)
	s_cmpk_lt_u32 s10, 0x100
	s_cselect_b64 s[10:11], -1, 0
	v_lshl_add_u64 v[154:155], s[0:1], 0, v[0:1]
	v_lshlrev_b32_e32 v0, 9, v146
	v_and_b32_e32 v0, 0x70000, v0
	v_lshlrev_b32_e32 v1, 12, v10
	v_or3_b32 v0, v8, v0, v1
	v_add_u32_e32 v156, v0, v9
	v_lshlrev_b32_e32 v0, 5, v12
	v_and_b32_e32 v0, 0xf0000, v0
	v_or3_b32 v0, v8, v0, v1
	v_add_u32_e32 v158, v0, v9
	s_add_i32 s56, 0, 0x10000
	s_add_i32 s57, 0, 0x14000
	v_mbcnt_lo_u32_b32 v0, -1, 0
	s_ashr_i32 s54, s18, 31
	s_mov_b32 s55, s18
	v_or_b32_e32 v170, s14, v11
	v_mov_b32_e32 v157, v149
	v_mov_b32_e32 v159, v149
	v_mov_b64_e32 v[160:161], 0x800
	v_mov_b64_e32 v[162:163], 0x7ff
	v_add_u32_e32 v171, s56, v169
	v_add_u32_e32 v172, s57, v169
	v_add_u32_e32 v173, 0, v3
	v_mbcnt_hi_u32_b32 v174, -1, v0
	v_mov_b32_e32 v175, 0x358637bd
	s_mov_b32 s58, 0x800000
	s_add_u32 s100, s42, 0x80080
	s_addc_u32 s101, s43, 0
	v_lshl_add_u64 v[220:221], s[100:101], 0, v[156:157]
	s_add_i32 m0, s41, 0xc000
	s_nop 0
	global_load_lds_dwordx4 v[220:221], off
	v_lshl_add_u64 v[220:221], s[100:101], 0, v[158:159]
	s_add_i32 m0, s41, 0xe000
	s_nop 0
	global_load_lds_dwordx4 v[220:221], off
	s_waitcnt vmcnt(0)
	s_barrier
	s_branch .LBB0_1135

;     __host__ __device__ bool next(int i, Unit& u) const { return map((long)i * G + c, u); }
; #define PG8_STAGE(bufoff, gbase, voff) do { _Pragma("unroll") for (int _i = 0; _i < 2; ++_i) \
;         __builtin_amdgcn_global_load_lds((const unsigned*)((const char*)(gbase) + (voff)[_i]), (PG8_LAS unsigned*)(lds + (bufoff) + ldsw + _i * 8192), 16, 0, 0); } while (0)
; #define PG8_LDA(dst, b, h) do { _Pragma("unroll") for (int m = 0; m < 4; ++m) _Pragma("unroll") for (int k = 0; k < 2; ++k) dst[m][k] = *(const PG8_LAS bf16x8*)(lds + PG8_SA(b, h) + aoff + m * 2048 + k * 1024); } while (0)
; #define PG8_LDB(dst, b, h) do { _Pragma("unroll") for (int n = 0; n < 2; ++n) _Pragma("unroll") for (int k = 0; k < 2; ++k) dst[n][k] = *(const PG8_LAS bf16x8*)(lds + PG8_SB(b, h) + boff + n * 2048 + k * 1024); } while (0)
; #define PG8_WAIT_V(n) asm volatile("s_waitcnt vmcnt(" #n ")" ::: "memory")
; #define PG8_WAIT_L(n) asm volatile("s_waitcnt lgkmcnt(" #n ")" ::: "memory")
; #define PG8_BAR __builtin_amdgcn_s_barrier()
; template <class Epi, class Sched, bool ALIGN_EPI = false, bool SP2 = false>
; __device__ __forceinline__ void gemm_phase(PG8_LAS unsigned char* lds, const Gemm g, const Sched& S, const Epi& E) {
;     ...
;         const bool has_next = S.next(ui + 1, nxt);
;         const char* nA = has_next ? PG8_UA(nxt) : cA; const char* nB = has_next ? PG8_UB(nxt) : cB;
;         const int nt = cur.nt;
;         for (int t = 0; t < nt; t += 2) {
;             const bool last = (t == nt - 2);
;             const char* a1 = cA + (size_t)(t + 1) * kstep;
;             const char* a2 = last ? nA : cA + (size_t)(t + 2) * kstep; const char* b2 = last ? nB : cB + (size_t)(t + 2) * kstep;
;             const char* a3 = a2 + kstep; const char* b3 = b2 + kstep;
;             if constexpr (SP2) {
;             PG8_LDB(B0, 0, 0); PG8_LDB(B1, 0, 1); PG8_SCHED; PG8_LDA(At, 0, 0); PG8_STAGE(PG8_SA(1, 1), a1 + hstep, voffA);
;             PG8_WAIT_V(8); PG8_WAIT_L(0); PG8_BAR; PG8_MMA(0, 0, At, B0); PG8_MMA(0, 1, At, B1); PG8_BAR; PG8_SCHED;
;     ...
; #pragma unroll
;         for (int a = 0; a < 2; ++a)
; #pragma unroll
;             for (int b = 0; b < 2; ++b)
; #pragma unroll
;                 for (int m = 0; m < 4; ++m)
; #pragma unroll
;                     for (int n = 0; n < 2; ++n) acc[a][b][m][n] = (f32x4){0.f, 0.f, 0.f, 0.f};
;         cur = nxt; cA = nA; cB = nB; ++ui;
.LBB0_1141:
	s_ashr_i32 s15, s14, 31
	s_lshl_b64 s[36:37], s[14:15], 20
	s_add_u32 s36, s30, s36
	s_addc_u32 s37, s31, s37
	s_and_b64 s[38:39], s[0:1], exec
	s_cselect_b32 s15, s37, s43
	s_cselect_b32 s60, s36, s42
	s_ashr_i32 s13, s12, 31
	s_lshl_b64 s[38:39], s[12:13], 20
	s_add_u32 s38, s28, s38
	s_addc_u32 s39, s29, s39
	s_and_b64 s[46:47], s[0:1], exec
	s_cselect_b32 s13, s39, s45
	s_cselect_b32 s61, s38, s44
	s_add_u32 s42, s42, 0x80080
	s_addc_u32 s43, s43, 0
	s_add_u32 s62, s44, 0x100
	v_mov_b32_e32 v0, 0
	s_addc_u32 s63, s45, 0
	s_mov_b32 s64, -2
	v_mov_b32_e32 v1, v0
	v_mov_b32_e32 v2, v0
	v_mov_b32_e32 v3, v0
	v_mov_b32_e32 v4, v0
	v_mov_b32_e32 v5, v0
	v_mov_b32_e32 v6, v0
	v_mov_b32_e32 v7, v0
	v_mov_b32_e32 v16, v0
	v_mov_b32_e32 v17, v0
	v_mov_b32_e32 v18, v0
	v_mov_b32_e32 v19, v0
	v_mov_b32_e32 v20, v0
	v_mov_b32_e32 v21, v0
	v_mov_b32_e32 v22, v0
	v_mov_b32_e32 v23, v0
	v_mov_b32_e32 v32, v0
	v_mov_b32_e32 v33, v0
	v_mov_b32_e32 v34, v0
	v_mov_b32_e32 v35, v0
	v_mov_b32_e32 v36, v0
	v_mov_b32_e32 v37, v0
	v_mov_b32_e32 v38, v0
	v_mov_b32_e32 v39, v0
	v_mov_b32_e32 v48, v0
	v_mov_b32_e32 v49, v0
	v_mov_b32_e32 v50, v0
	v_mov_b32_e32 v51, v0
	v_mov_b32_e32 v52, v0
	v_mov_b32_e32 v53, v0
	v_mov_b32_e32 v54, v0
	v_mov_b32_e32 v55, v0
	v_mov_b32_e32 v8, v0
	v_mov_b32_e32 v9, v0
	v_mov_b32_e32 v10, v0
	v_mov_b32_e32 v11, v0
	v_mov_b32_e32 v12, v0
	v_mov_b32_e32 v13, v0
	v_mov_b32_e32 v14, v0
	v_mov_b32_e32 v15, v0
	v_mov_b32_e32 v24, v0
	v_mov_b32_e32 v25, v0
	v_mov_b32_e32 v26, v0
	v_mov_b32_e32 v27, v0
	v_mov_b32_e32 v28, v0
	v_mov_b32_e32 v29, v0
	v_mov_b32_e32 v30, v0
	v_mov_b32_e32 v31, v0
	v_mov_b32_e32 v40, v0
	v_mov_b32_e32 v41, v0
	v_mov_b32_e32 v42, v0
	v_mov_b32_e32 v43, v0
	v_mov_b32_e32 v44, v0
	v_mov_b32_e32 v45, v0
	v_mov_b32_e32 v46, v0
	v_mov_b32_e32 v47, v0
	v_mov_b32_e32 v56, v0
	v_mov_b32_e32 v57, v0
	v_mov_b32_e32 v58, v0
	v_mov_b32_e32 v59, v0
	v_mov_b32_e32 v60, v0
	v_mov_b32_e32 v61, v0
	v_mov_b32_e32 v62, v0
	v_mov_b32_e32 v63, v0
	v_mov_b32_e32 v64, v0
	v_mov_b32_e32 v65, v0
	v_mov_b32_e32 v66, v0
	v_mov_b32_e32 v67, v0
	v_mov_b32_e32 v68, v0
	v_mov_b32_e32 v69, v0
	v_mov_b32_e32 v70, v0
	v_mov_b32_e32 v71, v0
	v_mov_b32_e32 v96, v0
	v_mov_b32_e32 v97, v0
	v_mov_b32_e32 v98, v0
	v_mov_b32_e32 v99, v0
	v_mov_b32_e32 v100, v0
	v_mov_b32_e32 v101, v0
	v_mov_b32_e32 v102, v0
	v_mov_b32_e32 v103, v0
	v_mov_b32_e32 v112, v0
	v_mov_b32_e32 v113, v0
	v_mov_b32_e32 v114, v0
	v_mov_b32_e32 v115, v0
	v_mov_b32_e32 v116, v0
	v_mov_b32_e32 v117, v0
	v_mov_b32_e32 v118, v0
	v_mov_b32_e32 v119, v0
	v_mov_b32_e32 v128, v0
	v_mov_b32_e32 v129, v0
	v_mov_b32_e32 v130, v0
	v_mov_b32_e32 v131, v0
	v_mov_b32_e32 v132, v0
	v_mov_b32_e32 v133, v0
	v_mov_b32_e32 v134, v0
	v_mov_b32_e32 v135, v0
	v_mov_b32_e32 v72, v0
	v_mov_b32_e32 v73, v0
	v_mov_b32_e32 v74, v0
	v_mov_b32_e32 v75, v0
	v_mov_b32_e32 v76, v0
	v_mov_b32_e32 v77, v0
	v_mov_b32_e32 v78, v0
	v_mov_b32_e32 v79, v0
	v_mov_b32_e32 v104, v0
	v_mov_b32_e32 v105, v0
	v_mov_b32_e32 v106, v0
	v_mov_b32_e32 v107, v0
	v_mov_b32_e32 v108, v0
	v_mov_b32_e32 v109, v0
	v_mov_b32_e32 v110, v0
	v_mov_b32_e32 v111, v0
	v_mov_b32_e32 v120, v0
	v_mov_b32_e32 v121, v0
	v_mov_b32_e32 v122, v0
	v_mov_b32_e32 v123, v0
	v_mov_b32_e32 v124, v0
	v_mov_b32_e32 v125, v0
	v_mov_b32_e32 v126, v0
	v_mov_b32_e32 v127, v0
	v_mov_b32_e32 v136, v0
	v_mov_b32_e32 v137, v0
	v_mov_b32_e32 v138, v0
	v_mov_b32_e32 v139, v0
	v_mov_b32_e32 v140, v0
	v_mov_b32_e32 v141, v0
	v_mov_b32_e32 v142, v0
	v_mov_b32_e32 v143, v0
	ds_read_b128 v[80:83], v171
	ds_read_b128 v[84:87], v171 offset:1024
	ds_read_b128 v[88:91], v171 offset:2048
	ds_read_b128 v[92:95], v171 offset:3072
	ds_read_b128 v[164:167], v172
	ds_read_b128 v[176:179], v172 offset:1024
	ds_read_b128 v[180:183], v172 offset:2048
	ds_read_b128 v[184:187], v172 offset:3072
	s_add_u32 s44, s42, 0xfff80080
	s_addc_u32 s45, s43, -1
	s_cmp_eq_u32 s64, 28
	s_cselect_b32 s47, s15, s45
	s_cselect_b32 s46, s60, s44
	s_cselect_b32 s45, s13, s63
	s_cselect_b32 s44, s61, s62
	v_lshl_add_u64 v[220:221], s[42:43], 0, v[156:157]
	s_add_i32 m0, s41, 0xc000
	ds_read_b128 v[188:191], v173
	ds_read_b128 v[192:195], v173 offset:1024
	ds_read_b128 v[196:199], v173 offset:2048
	ds_read_b128 v[200:203], v173 offset:3072
	ds_read_b128 v[204:207], v173 offset:4096
	ds_read_b128 v[208:211], v173 offset:5120
	ds_read_b128 v[212:215], v173 offset:6144
	ds_read_b128 v[216:219], v173 offset:7168
	v_lshl_add_u64 v[220:221], s[42:43], 0, v[158:159]
	s_add_i32 m0, s41, 0xe000
	s_nop 0
	s_waitcnt lgkmcnt(0)
	s_barrier
; #define PG8_STAGE(bufoff, gbase, voff) do { _Pragma("unroll") for (int _i = 0; _i < 2; ++_i) \
;         __builtin_amdgcn_global_load_lds((const unsigned*)((const char*)(gbase) + (voff)[_i]), (PG8_LAS unsigned*)(lds + (bufoff) + ldsw + _i * 8192), 16, 0, 0); } while (0)
; #define PG8_LDA(dst, b, h) do { _Pragma("unroll") for (int m = 0; m < 4; ++m) _Pragma("unroll") for (int k = 0; k < 2; ++k) dst[m][k] = *(const PG8_LAS bf16x8*)(lds + PG8_SA(b, h) + aoff + m * 2048 + k * 1024); } while (0)
; #define PG8_LDB(dst, b, h) do { _Pragma("unroll") for (int n = 0; n < 2; ++n) _Pragma("unroll") for (int k = 0; k < 2; ++k) dst[n][k] = *(const PG8_LAS bf16x8*)(lds + PG8_SB(b, h) + boff + n * 2048 + k * 1024); } while (0)
; #define PG8_MMA(ai, bj, At, Bt) do { __builtin_amdgcn_s_setprio(1); _Pragma("unroll") for (int m = 0; m < 4; ++m) _Pragma("unroll") for (int n = 0; n < 2; ++n) _Pragma("unroll") for (int k = 0; k < 2; ++k) \
;         acc[ai][bj][m][n] = __builtin_amdgcn_mfma_f32_16x16x32_bf16(Bt[n][k], At[m][k], acc[ai][bj][m][n], 0, 0, 0); __builtin_amdgcn_s_setprio(0); } while (0)
; #define PG8_WAIT_V(n) asm volatile("s_waitcnt vmcnt(" #n ")" ::: "memory")
; #define PG8_WAIT_L(n) asm volatile("s_waitcnt lgkmcnt(" #n ")" ::: "memory")
; #define PG8_BAR __builtin_amdgcn_s_barrier()
; #define PG8_SCHED __builtin_amdgcn_sched_barrier(0)
; template <class Epi, class Sched, bool ALIGN_EPI = false, bool SP2 = false>
; __device__ __forceinline__ void gemm_phase(PG8_LAS unsigned char* lds, const Gemm g, const Sched& S, const Epi& E) {
;     ...
;             PG8_LDB(B0, 0, 0); PG8_LDB(B1, 0, 1); PG8_SCHED; PG8_LDA(At, 0, 0); PG8_STAGE(PG8_SA(1, 1), a1 + hstep, voffA);
;             PG8_WAIT_V(8); PG8_WAIT_L(0); PG8_BAR; PG8_MMA(0, 0, At, B0); PG8_MMA(0, 1, At, B1); PG8_BAR; PG8_SCHED;
;             PG8_LDA(At, 0, 1); PG8_STAGE(PG8_SB(0, 0), b2, voffB); PG8_STAGE(PG8_SB(0, 1), b2 + hstep, voffB); PG8_STAGE(PG8_SA(0, 0), a2, voffA);
;             PG8_WAIT_V(8); PG8_WAIT_L(0); PG8_BAR; PG8_MMA(1, 0, At, B0); PG8_MMA(1, 1, At, B1); PG8_BAR; PG8_SCHED;
	s_setprio 1
	s_waitcnt lgkmcnt(0)
	v_mfma_f32_16x16x32_bf16 v[140:143], v[80:83], v[188:191], v[140:143]
	v_mfma_f32_16x16x32_bf16 v[136:139], v[88:91], v[188:191], v[136:139]
	v_mfma_f32_16x16x32_bf16 v[124:127], v[80:83], v[196:199], v[124:127]
	v_mfma_f32_16x16x32_bf16 v[120:123], v[88:91], v[196:199], v[120:123]
	v_mfma_f32_16x16x32_bf16 v[108:111], v[80:83], v[204:207], v[108:111]
	v_mfma_f32_16x16x32_bf16 v[104:107], v[88:91], v[204:207], v[104:107]
	v_mfma_f32_16x16x32_bf16 v[76:79], v[80:83], v[212:215], v[76:79]
	v_mfma_f32_16x16x32_bf16 v[72:75], v[88:91], v[212:215], v[72:75]
	v_mfma_f32_16x16x32_bf16 v[140:143], v[84:87], v[192:195], v[140:143]
	v_mfma_f32_16x16x32_bf16 v[136:139], v[92:95], v[192:195], v[136:139]
	v_mfma_f32_16x16x32_bf16 v[124:127], v[84:87], v[200:203], v[124:127]
	v_mfma_f32_16x16x32_bf16 v[120:123], v[92:95], v[200:203], v[120:123]
	v_mfma_f32_16x16x32_bf16 v[108:111], v[84:87], v[208:211], v[108:111]
	v_mfma_f32_16x16x32_bf16 v[104:107], v[92:95], v[208:211], v[104:107]
	v_mfma_f32_16x16x32_bf16 v[76:79], v[84:87], v[216:219], v[76:79]
	v_mfma_f32_16x16x32_bf16 v[72:75], v[92:95], v[216:219], v[72:75]
	s_setprio 0
	s_setprio 1
	v_mfma_f32_16x16x32_bf16 v[132:135], v[164:167], v[188:191], v[132:135]
	v_mfma_f32_16x16x32_bf16 v[128:131], v[180:183], v[188:191], v[128:131]
	v_mfma_f32_16x16x32_bf16 v[116:119], v[164:167], v[196:199], v[116:119]
	v_mfma_f32_16x16x32_bf16 v[112:115], v[180:183], v[196:199], v[112:115]
	v_mfma_f32_16x16x32_bf16 v[100:103], v[164:167], v[204:207], v[100:103]
	v_mfma_f32_16x16x32_bf16 v[96:99], v[180:183], v[204:207], v[96:99]
	v_mfma_f32_16x16x32_bf16 v[68:71], v[164:167], v[212:215], v[68:71]
	v_mfma_f32_16x16x32_bf16 v[64:67], v[180:183], v[212:215], v[64:67]
	v_mfma_f32_16x16x32_bf16 v[132:135], v[176:179], v[192:195], v[132:135]
	v_mfma_f32_16x16x32_bf16 v[128:131], v[184:187], v[192:195], v[128:131]
	v_mfma_f32_16x16x32_bf16 v[116:119], v[176:179], v[200:203], v[116:119]
	v_mfma_f32_16x16x32_bf16 v[112:115], v[184:187], v[200:203], v[112:115]
	v_mfma_f32_16x16x32_bf16 v[100:103], v[176:179], v[208:211], v[100:103]
	v_mfma_f32_16x16x32_bf16 v[96:99], v[184:187], v[208:211], v[96:99]
	v_mfma_f32_16x16x32_bf16 v[68:71], v[176:179], v[216:219], v[68:71]
	v_mfma_f32_16x16x32_bf16 v[64:67], v[184:187], v[216:219], v[64:67]
	s_setprio 0
	s_barrier
	s_add_i32 s65, s56, s33
	v_lshl_add_u64 v[220:221], s[44:45], 0, v[148:149]
	s_mov_b32 m0, s65
	ds_read_b128 v[188:191], v173 offset:16384
	ds_read_b128 v[192:195], v173 offset:17408
	ds_read_b128 v[196:199], v173 offset:18432
	ds_read_b128 v[200:203], v173 offset:19456
	ds_read_b128 v[204:207], v173 offset:20480
	ds_read_b128 v[208:211], v173 offset:21504
	ds_read_b128 v[212:215], v173 offset:22528
	ds_read_b128 v[216:219], v173 offset:23552
	global_load_lds_dwordx4 v[220:221], off
	s_add_i32 m0, s65, 0x2000
	s_add_u32 s66, s44, 0x80000
	v_lshl_add_u64 v[222:223], s[44:45], 0, v[152:153]
	s_addc_u32 s67, s45, 0
	s_add_i32 s65, s57, s33
	global_load_lds_dwordx4 v[222:223], off
	v_lshl_add_u64 v[224:225], s[66:67], 0, v[148:149]
	s_mov_b32 m0, s65
	v_lshl_add_u64 v[226:227], s[46:47], 0, v[150:151]
	global_load_lds_dwordx4 v[224:225], off
	v_lshl_add_u64 v[224:225], s[66:67], 0, v[152:153]
	s_add_i32 m0, s65, 0x2000
	s_nop 0
	global_load_lds_dwordx4 v[224:225], off
	v_lshl_add_u64 v[224:225], s[46:47], 0, v[144:145]
	s_mov_b32 m0, s41
	s_nop 0
	global_load_lds_dwordx4 v[224:225], off
	s_mov_b32 m0, s48
	s_nop 0
	global_load_lds_dwordx4 v[226:227], off
	s_waitcnt lgkmcnt(0)
	s_barrier
	s_setprio 1
	s_waitcnt lgkmcnt(0)
	v_mfma_f32_16x16x32_bf16 v[60:63], v[80:83], v[188:191], v[60:63]
	v_mfma_f32_16x16x32_bf16 v[56:59], v[88:91], v[188:191], v[56:59]
	v_mfma_f32_16x16x32_bf16 v[44:47], v[80:83], v[196:199], v[44:47]
	v_mfma_f32_16x16x32_bf16 v[40:43], v[88:91], v[196:199], v[40:43]
	v_mfma_f32_16x16x32_bf16 v[28:31], v[80:83], v[204:207], v[28:31]
	v_mfma_f32_16x16x32_bf16 v[24:27], v[88:91], v[204:207], v[24:27]
	v_mfma_f32_16x16x32_bf16 v[12:15], v[80:83], v[212:215], v[12:15]
	v_mfma_f32_16x16x32_bf16 v[8:11], v[88:91], v[212:215], v[8:11]
	v_mfma_f32_16x16x32_bf16 v[60:63], v[84:87], v[192:195], v[60:63]
	v_mfma_f32_16x16x32_bf16 v[56:59], v[92:95], v[192:195], v[56:59]
	v_mfma_f32_16x16x32_bf16 v[44:47], v[84:87], v[200:203], v[44:47]
	v_mfma_f32_16x16x32_bf16 v[40:43], v[92:95], v[200:203], v[40:43]
	v_mfma_f32_16x16x32_bf16 v[28:31], v[84:87], v[208:211], v[28:31]
	v_mfma_f32_16x16x32_bf16 v[24:27], v[92:95], v[208:211], v[24:27]
	v_mfma_f32_16x16x32_bf16 v[12:15], v[84:87], v[216:219], v[12:15]
	v_mfma_f32_16x16x32_bf16 v[8:11], v[92:95], v[216:219], v[8:11]
	s_setprio 0
	s_setprio 1
	v_mfma_f32_16x16x32_bf16 v[52:55], v[164:167], v[188:191], v[52:55]
	v_mfma_f32_16x16x32_bf16 v[48:51], v[180:183], v[188:191], v[48:51]
	v_mfma_f32_16x16x32_bf16 v[36:39], v[164:167], v[196:199], v[36:39]
	v_mfma_f32_16x16x32_bf16 v[32:35], v[180:183], v[196:199], v[32:35]
	v_mfma_f32_16x16x32_bf16 v[20:23], v[164:167], v[204:207], v[20:23]
	v_mfma_f32_16x16x32_bf16 v[16:19], v[180:183], v[204:207], v[16:19]
	v_mfma_f32_16x16x32_bf16 v[4:7], v[164:167], v[212:215], v[4:7]
	v_mfma_f32_16x16x32_bf16 v[0:3], v[180:183], v[212:215], v[0:3]
	v_mfma_f32_16x16x32_bf16 v[52:55], v[176:179], v[192:195], v[52:55]
	v_mfma_f32_16x16x32_bf16 v[48:51], v[184:187], v[192:195], v[48:51]
	v_mfma_f32_16x16x32_bf16 v[36:39], v[176:179], v[200:203], v[36:39]
	v_mfma_f32_16x16x32_bf16 v[32:35], v[184:187], v[200:203], v[32:35]
	v_mfma_f32_16x16x32_bf16 v[20:23], v[176:179], v[208:211], v[20:23]
	v_mfma_f32_16x16x32_bf16 v[16:19], v[184:187], v[208:211], v[16:19]
	v_mfma_f32_16x16x32_bf16 v[4:7], v[176:179], v[216:219], v[4:7]
	v_mfma_f32_16x16x32_bf16 v[0:3], v[184:187], v[216:219], v[0:3]
	s_setprio 0
	s_barrier
; #define PG8_STAGE(bufoff, gbase, voff) do { _Pragma("unroll") for (int _i = 0; _i < 2; ++_i) \
;         __builtin_amdgcn_global_load_lds((const unsigned*)((const char*)(gbase) + (voff)[_i]), (PG8_LAS unsigned*)(lds + (bufoff) + ldsw + _i * 8192), 16, 0, 0); } while (0)
; #define PG8_LDA(dst, b, h) do { _Pragma("unroll") for (int m = 0; m < 4; ++m) _Pragma("unroll") for (int k = 0; k < 2; ++k) dst[m][k] = *(const PG8_LAS bf16x8*)(lds + PG8_SA(b, h) + aoff + m * 2048 + k * 1024); } while (0)
; #define PG8_LDB(dst, b, h) do { _Pragma("unroll") for (int n = 0; n < 2; ++n) _Pragma("unroll") for (int k = 0; k < 2; ++k) dst[n][k] = *(const PG8_LAS bf16x8*)(lds + PG8_SB(b, h) + boff + n * 2048 + k * 1024); } while (0)
; #define PG8_MMA(ai, bj, At, Bt) do { __builtin_amdgcn_s_setprio(1); _Pragma("unroll") for (int m = 0; m < 4; ++m) _Pragma("unroll") for (int n = 0; n < 2; ++n) _Pragma("unroll") for (int k = 0; k < 2; ++k) \
;         acc[ai][bj][m][n] = __builtin_amdgcn_mfma_f32_16x16x32_bf16(Bt[n][k], At[m][k], acc[ai][bj][m][n], 0, 0, 0); __builtin_amdgcn_s_setprio(0); } while (0)
; #define PG8_WAIT_V(n) asm volatile("s_waitcnt vmcnt(" #n ")" ::: "memory")
; #define PG8_WAIT_L(n) asm volatile("s_waitcnt lgkmcnt(" #n ")" ::: "memory")
; #define PG8_BAR __builtin_amdgcn_s_barrier()
; #define PG8_SCHED __builtin_amdgcn_sched_barrier(0)
; template <class Epi, class Sched, bool ALIGN_EPI = false, bool SP2 = false>
; __device__ __forceinline__ void gemm_phase(PG8_LAS unsigned char* lds, const Gemm g, const Sched& S, const Epi& E) {
;     ...
;             PG8_LDB(B0, 1, 0); PG8_LDB(B1, 1, 1); PG8_SCHED; PG8_LDA(At, 1, 0); PG8_STAGE(PG8_SA(0, 1), a2 + hstep, voffA);
;             PG8_WAIT_V(8); PG8_WAIT_L(0); PG8_BAR; PG8_MMA(0, 0, At, B0); PG8_MMA(0, 1, At, B1); PG8_BAR; PG8_SCHED;
;             PG8_LDA(At, 1, 1); PG8_STAGE(PG8_SB(1, 0), b3, voffB); PG8_STAGE(PG8_SB(1, 1), b3 + hstep, voffB); PG8_STAGE(PG8_SA(1, 0), a3, voffA);
;             PG8_WAIT_V(8); PG8_WAIT_L(0); PG8_BAR; PG8_MMA(1, 0, At, B0); PG8_MMA(1, 1, At, B1); PG8_BAR; PG8_SCHED;
	s_add_i32 s65, 0, 0x18000
	s_add_i32 s66, 0, 0x1c000
	v_add_u32_e32 v92, s65, v169
	v_add_u32_e32 v184, s66, v169
	ds_read_b128 v[80:83], v92
	ds_read_b128 v[84:87], v92 offset:1024
	ds_read_b128 v[88:91], v92 offset:2048
	ds_read_b128 v[92:95], v92 offset:3072
	ds_read_b128 v[164:167], v184
	ds_read_b128 v[176:179], v184 offset:1024
	ds_read_b128 v[180:183], v184 offset:2048
	ds_read_b128 v[184:187], v184 offset:3072
	s_add_u32 s46, s46, 0x80000
	s_addc_u32 s47, s47, 0
	s_mov_b32 m0, s49
	v_lshl_add_u64 v[228:229], s[46:47], 0, v[144:145]
	ds_read_b128 v[188:191], v173 offset:32768
	ds_read_b128 v[192:195], v173 offset:33792
	ds_read_b128 v[196:199], v173 offset:34816
	ds_read_b128 v[200:203], v173 offset:35840
	ds_read_b128 v[204:207], v173 offset:36864
	ds_read_b128 v[208:211], v173 offset:37888
	ds_read_b128 v[212:215], v173 offset:38912
	ds_read_b128 v[216:219], v173 offset:39936
	global_load_lds_dwordx4 v[228:229], off
	v_lshl_add_u64 v[228:229], s[46:47], 0, v[150:151]
	s_mov_b32 m0, s50
	s_nop 0
	global_load_lds_dwordx4 v[228:229], off
	s_waitcnt lgkmcnt(0)
	s_barrier
	s_setprio 1
	s_waitcnt lgkmcnt(0)
	v_mfma_f32_16x16x32_bf16 v[140:143], v[80:83], v[188:191], v[140:143]
	v_mfma_f32_16x16x32_bf16 v[136:139], v[88:91], v[188:191], v[136:139]
	v_mfma_f32_16x16x32_bf16 v[124:127], v[80:83], v[196:199], v[124:127]
	v_mfma_f32_16x16x32_bf16 v[120:123], v[88:91], v[196:199], v[120:123]
	v_mfma_f32_16x16x32_bf16 v[108:111], v[80:83], v[204:207], v[108:111]
	v_mfma_f32_16x16x32_bf16 v[104:107], v[88:91], v[204:207], v[104:107]
	v_mfma_f32_16x16x32_bf16 v[76:79], v[80:83], v[212:215], v[76:79]
	v_mfma_f32_16x16x32_bf16 v[72:75], v[88:91], v[212:215], v[72:75]
	v_mfma_f32_16x16x32_bf16 v[140:143], v[84:87], v[192:195], v[140:143]
	v_mfma_f32_16x16x32_bf16 v[136:139], v[92:95], v[192:195], v[136:139]
	v_mfma_f32_16x16x32_bf16 v[124:127], v[84:87], v[200:203], v[124:127]
	v_mfma_f32_16x16x32_bf16 v[120:123], v[92:95], v[200:203], v[120:123]
	v_mfma_f32_16x16x32_bf16 v[108:111], v[84:87], v[208:211], v[108:111]
	v_mfma_f32_16x16x32_bf16 v[104:107], v[92:95], v[208:211], v[104:107]
	v_mfma_f32_16x16x32_bf16 v[76:79], v[84:87], v[216:219], v[76:79]
	v_mfma_f32_16x16x32_bf16 v[72:75], v[92:95], v[216:219], v[72:75]
	s_setprio 0
	s_setprio 1
	v_mfma_f32_16x16x32_bf16 v[132:135], v[164:167], v[188:191], v[132:135]
	v_mfma_f32_16x16x32_bf16 v[128:131], v[180:183], v[188:191], v[128:131]
	v_mfma_f32_16x16x32_bf16 v[116:119], v[164:167], v[196:199], v[116:119]
	v_mfma_f32_16x16x32_bf16 v[112:115], v[180:183], v[196:199], v[112:115]
	v_mfma_f32_16x16x32_bf16 v[100:103], v[164:167], v[204:207], v[100:103]
	v_mfma_f32_16x16x32_bf16 v[96:99], v[180:183], v[204:207], v[96:99]
	v_mfma_f32_16x16x32_bf16 v[68:71], v[164:167], v[212:215], v[68:71]
	v_mfma_f32_16x16x32_bf16 v[64:67], v[180:183], v[212:215], v[64:67]
	v_mfma_f32_16x16x32_bf16 v[132:135], v[176:179], v[192:195], v[132:135]
	v_mfma_f32_16x16x32_bf16 v[128:131], v[184:187], v[192:195], v[128:131]
	v_mfma_f32_16x16x32_bf16 v[116:119], v[176:179], v[200:203], v[116:119]
	v_mfma_f32_16x16x32_bf16 v[112:115], v[184:187], v[200:203], v[112:115]
	v_mfma_f32_16x16x32_bf16 v[100:103], v[176:179], v[208:211], v[100:103]
	v_mfma_f32_16x16x32_bf16 v[96:99], v[184:187], v[208:211], v[96:99]
	v_mfma_f32_16x16x32_bf16 v[68:71], v[176:179], v[216:219], v[68:71]
	v_mfma_f32_16x16x32_bf16 v[64:67], v[184:187], v[216:219], v[64:67]
	s_setprio 0
	s_barrier
	s_add_i32 s46, s65, s33
	v_lshl_add_u64 v[220:221], v[220:221], 0, s[8:9]
	s_mov_b32 m0, s46
	ds_read_b128 v[188:191], v173 offset:49152
	ds_read_b128 v[192:195], v173 offset:50176
	ds_read_b128 v[196:199], v173 offset:51200
	ds_read_b128 v[200:203], v173 offset:52224
	ds_read_b128 v[204:207], v173 offset:53248
	ds_read_b128 v[208:211], v173 offset:54272
	ds_read_b128 v[212:215], v173 offset:55296
	ds_read_b128 v[216:219], v173 offset:56320
	global_load_lds_dwordx4 v[220:221], off
	s_add_i32 m0, s46, 0x2000
	s_add_u32 s44, s44, 0x80080
	v_lshl_add_u64 v[220:221], v[222:223], 0, s[8:9]
	s_addc_u32 s45, s45, 0
	s_add_i32 s46, s66, s33
	global_load_lds_dwordx4 v[220:221], off
	v_lshl_add_u64 v[220:221], s[44:45], 0, v[148:149]
	s_mov_b32 m0, s46
	s_nop 0
	global_load_lds_dwordx4 v[220:221], off
	v_lshl_add_u64 v[220:221], s[44:45], 0, v[152:153]
	s_add_i32 m0, s46, 0x2000
	s_nop 0
	global_load_lds_dwordx4 v[220:221], off
	v_lshl_add_u64 v[220:221], v[224:225], 0, s[8:9]
	s_mov_b32 m0, s52
	s_nop 0
	global_load_lds_dwordx4 v[220:221], off
	v_lshl_add_u64 v[220:221], v[226:227], 0, s[8:9]
	s_mov_b32 m0, s53
	s_nop 0
	global_load_lds_dwordx4 v[220:221], off
	s_waitcnt vmcnt(8)
	s_waitcnt lgkmcnt(0)
	s_barrier
	s_setprio 1
	s_waitcnt lgkmcnt(0)
	v_mfma_f32_16x16x32_bf16 v[60:63], v[80:83], v[188:191], v[60:63]
	v_mfma_f32_16x16x32_bf16 v[56:59], v[88:91], v[188:191], v[56:59]
	v_mfma_f32_16x16x32_bf16 v[44:47], v[80:83], v[196:199], v[44:47]
	v_mfma_f32_16x16x32_bf16 v[40:43], v[88:91], v[196:199], v[40:43]
	v_mfma_f32_16x16x32_bf16 v[28:31], v[80:83], v[204:207], v[28:31]
	v_mfma_f32_16x16x32_bf16 v[24:27], v[88:91], v[204:207], v[24:27]
	v_mfma_f32_16x16x32_bf16 v[12:15], v[80:83], v[212:215], v[12:15]
	v_mfma_f32_16x16x32_bf16 v[8:11], v[88:91], v[212:215], v[8:11]
	v_mfma_f32_16x16x32_bf16 v[60:63], v[84:87], v[192:195], v[60:63]
	v_mfma_f32_16x16x32_bf16 v[56:59], v[92:95], v[192:195], v[56:59]
	v_mfma_f32_16x16x32_bf16 v[44:47], v[84:87], v[200:203], v[44:47]
	v_mfma_f32_16x16x32_bf16 v[40:43], v[92:95], v[200:203], v[40:43]
	v_mfma_f32_16x16x32_bf16 v[28:31], v[84:87], v[208:211], v[28:31]
	v_mfma_f32_16x16x32_bf16 v[24:27], v[92:95], v[208:211], v[24:27]
	v_mfma_f32_16x16x32_bf16 v[12:15], v[84:87], v[216:219], v[12:15]
	v_mfma_f32_16x16x32_bf16 v[8:11], v[92:95], v[216:219], v[8:11]
	s_setprio 0
	s_setprio 1
	v_mfma_f32_16x16x32_bf16 v[52:55], v[164:167], v[188:191], v[52:55]
	v_mfma_f32_16x16x32_bf16 v[48:51], v[180:183], v[188:191], v[48:51]
	v_mfma_f32_16x16x32_bf16 v[36:39], v[164:167], v[196:199], v[36:39]
	v_mfma_f32_16x16x32_bf16 v[32:35], v[180:183], v[196:199], v[32:35]
	v_mfma_f32_16x16x32_bf16 v[20:23], v[164:167], v[204:207], v[20:23]
	v_mfma_f32_16x16x32_bf16 v[16:19], v[180:183], v[204:207], v[16:19]
	v_mfma_f32_16x16x32_bf16 v[4:7], v[164:167], v[212:215], v[4:7]
	v_mfma_f32_16x16x32_bf16 v[0:3], v[180:183], v[212:215], v[0:3]
	v_mfma_f32_16x16x32_bf16 v[52:55], v[176:179], v[192:195], v[52:55]
	v_mfma_f32_16x16x32_bf16 v[48:51], v[184:187], v[192:195], v[48:51]
	v_mfma_f32_16x16x32_bf16 v[36:39], v[176:179], v[200:203], v[36:39]
	v_mfma_f32_16x16x32_bf16 v[32:35], v[184:187], v[200:203], v[32:35]
	v_mfma_f32_16x16x32_bf16 v[20:23], v[176:179], v[208:211], v[20:23]
	v_mfma_f32_16x16x32_bf16 v[16:19], v[184:187], v[208:211], v[16:19]
	v_mfma_f32_16x16x32_bf16 v[4:7], v[176:179], v[216:219], v[4:7]
	v_mfma_f32_16x16x32_bf16 v[0:3], v[184:187], v[216:219], v[0:3]
	s_setprio 0
	s_barrier
	s_add_i32 s64, s64, 2
	s_add_u32 s42, s42, 0x100
	s_addc_u32 s43, s43, 0
	s_add_u32 s62, s62, 0x100
	s_addc_u32 s63, s63, 0

; #define PG8_STAGE(bufoff, gbase, voff) do { _Pragma("unroll") for (int _i = 0; _i < 2; ++_i) \
;         __builtin_amdgcn_global_load_lds((const unsigned*)((const char*)(gbase) + (voff)[_i]), (PG8_LAS unsigned*)(lds + (bufoff) + ldsw + _i * 8192), 16, 0, 0); } while (0)
; #define PG8_LDA(dst, b, h) do { _Pragma("unroll") for (int m = 0; m < 4; ++m) _Pragma("unroll") for (int k = 0; k < 2; ++k) dst[m][k] = *(const PG8_LAS bf16x8*)(lds + PG8_SA(b, h) + aoff + m * 2048 + k * 1024); } while (0)
; #define PG8_LDB(dst, b, h) do { _Pragma("unroll") for (int n = 0; n < 2; ++n) _Pragma("unroll") for (int k = 0; k < 2; ++k) dst[n][k] = *(const PG8_LAS bf16x8*)(lds + PG8_SB(b, h) + boff + n * 2048 + k * 1024); } while (0)
; #define PG8_SCHED __builtin_amdgcn_sched_barrier(0)
;     __device__ __forceinline__ void operator()(const f32x4 (&acc)[2][2][4][2], const Unit& u, int wr, int wc, int fr, int fq) const {
;         const int row0 = u.pm * BM + wr * 64 + fr, col0 = u.pn * BM + wc * 32 + 8 * fq;
;         const int mr = u.pm < (ML / BM) ? u.pm / (SEQ / BM) : BATCH;
;         f32x4 bv[2][2];
; #pragma unroll
;         for (int bj = 0; bj < 2; ++bj)
; #pragma unroll
;             for (int n = 0; n < 2; ++n) bv[bj][n] = *(const f32x4*)(shw + (size_t)mr * FF + col0 + bj * HALF + 4 * n);
; template <class Epi, class Sched, bool ALIGN_EPI = false, bool SP2 = false>
; __device__ __forceinline__ void gemm_phase(PG8_LAS unsigned char* lds, const Gemm g, const Sched& S, const Epi& E) {
;     ...
;             PG8_LDB(B0, 0, 0); PG8_LDB(B1, 0, 1); PG8_SCHED; PG8_LDA(At, 0, 0); PG8_STAGE(PG8_SA(1, 1), a1 + hstep, voffA);
.LBB0_1145:
	s_add_u32 s100, s60, 0x80080
	s_addc_u32 s101, s15, 0
	v_lshl_add_u64 v[220:221], s[100:101], 0, v[156:157]
	s_add_i32 m0, s41, 0xc000
	s_nop 0
	global_load_lds_dwordx4 v[220:221], off
	v_lshl_add_u64 v[220:221], s[100:101], 0, v[158:159]
	s_add_i32 m0, s41, 0xe000
	s_nop 0
	global_load_lds_dwordx4 v[220:221], off
	s_cmp_gt_i32 s40, 63
	s_mov_b64 s[42:43], 0x10000
	s_cbranch_scc1 .LBB0_1147
	s_ashr_i32 s13, s40, 31
	s_lshr_b32 s13, s13, 29
	s_add_i32 s13, s40, s13
	s_ashr_i32 s42, s13, 3
	s_ashr_i32 s43, s42, 31
	s_lshl_b64 s[42:43], s[42:43], 13
